# H4 + in-proj f-tile epilogue: second lower-bound load pair hoisted next to the first (one memory round trip and one vmcnt(0) less per f tile)
# baseline (speedup 1.0000x reference)
;     __device__ __forceinline__ void operator()(const AccT& acc, const pg8::Unit& u, int wr, int wc, int fr, int fq) const {
;     ...
;         if (pn < 8) {
; #pragma unroll
;             for (int bj = 0; bj < 2; ++bj) {
;                 const int col = pn * 256 + bj * 128 + cl;
;                 const f32x4 l0 = *(const f32x4*)(lb + col), l1 = *(const f32x4*)(lb + col + 4);
; #pragma unroll
;                 for (int ai = 0; ai < 2; ++ai)
; #pragma unroll
;                     for (int m = 0; m < 4; ++m) {
;                         const f32x4 a = acc[ai][bj][m][0], b = acc[ai][bj][m][1]; float g[8];
; #pragma unroll
;                         for (int j = 0; j < 4; ++j) { g[j] = (1.f - l0[j]) * __builtin_amdgcn_rcpf(1.f + __expf(a[j])); g[4 + j] = (1.f - l1[j]) * __builtin_amdgcn_rcpf(1.f + __expf(b[j])); }
;                         u32x4 w; w.x = pk_h2(g[0], g[1]); w.y = pk_h2(g[2], g[3]); w.z = pk_h2(g[4], g[5]); w.w = pk_h2(g[6], g[7]);
;                         *(u32x4*)(G + (size_t)(row0 + ai * 128 + m * 16) * 2048 + col) = w;
;                     }
.LBB0_277:
	s_andn2_b64 vcc, exec, s[68:69]
	s_cbranch_vccnz .LBB0_231
	v_lshl_or_b32 v128, s66, 8, v146
	v_ashrrev_i32_e32 v129, 31, v128
	v_lshl_add_u64 v[134:135], v[128:129], 2, s[20:21]
	global_load_dwordx4 v[130:133], v[134:135], off
	global_load_dwordx4 v[156:159], v[134:135], off offset:16
	global_load_dwordx4 v[226:229], v[134:135], off offset:512
	global_load_dwordx4 v[230:233], v[134:135], off offset:528
	v_mul_f32_e32 v124, 0x3fb8aa3b, v124
	v_mul_f32_e32 v120, 0x3fb8aa3b, v120
	v_mul_f32_e32 v125, 0x3fb8aa3b, v125
	v_mul_f32_e32 v121, 0x3fb8aa3b, v121
	v_ashrrev_i32_e32 v155, 31, v154
	v_mul_f32_e32 v134, 0x3fb8aa3b, v112
	v_mul_f32_e32 v135, 0x3fb8aa3b, v113
	v_mul_f32_e32 v114, 0x3fb8aa3b, v114
	v_exp_f32_e32 v124, v124
	v_exp_f32_e32 v120, v120
	v_exp_f32_e32 v125, v125
	v_exp_f32_e32 v121, v121
	v_lshlrev_b64 v[112:113], 12, v[154:155]
	v_exp_f32_e32 v144, v134
	v_exp_f32_e32 v155, v135
	v_exp_f32_e32 v114, v114
	v_mul_f32_e32 v122, 0x3fb8aa3b, v122
	v_mul_f32_e32 v123, 0x3fb8aa3b, v123
	v_mul_f32_e32 v126, 0x3fb8aa3b, v126
	v_mul_f32_e32 v127, 0x3fb8aa3b, v127
	v_mul_f32_e32 v119, 0x3fb8aa3b, v119
	v_mul_f32_e32 v115, 0x3fb8aa3b, v115
	v_exp_f32_e32 v122, v122
	v_exp_f32_e32 v123, v123
	v_exp_f32_e32 v126, v126
	v_exp_f32_e32 v127, v127
	v_exp_f32_e32 v165, v119
	v_exp_f32_e32 v168, v115
	v_add_f32_e32 v115, 1.0, v124
	v_add_f32_e32 v119, 1.0, v120
	v_add_f32_e32 v120, 1.0, v125
	v_mul_f32_e32 v118, 0x3fb8aa3b, v118
	v_lshlrev_b64 v[134:135], 1, v[128:129]
	v_add_f32_e32 v121, 1.0, v121
	v_add_f32_e32 v129, 1.0, v144
	v_add_f32_e32 v144, 1.0, v155
	v_add_f32_e32 v155, 1.0, v114
	v_rcp_f32_e32 v114, v115
	v_rcp_f32_e32 v115, v120
	v_mul_f32_e32 v116, 0x3fb8aa3b, v116
	v_mul_f32_e32 v117, 0x3fb8aa3b, v117
	v_exp_f32_e32 v118, v118
	v_rcp_f32_e32 v124, v119
	v_rcp_f32_e32 v125, v121
	v_exp_f32_e32 v116, v116
	v_exp_f32_e32 v117, v117
	v_add_f32_e32 v122, 1.0, v122
	v_add_f32_e32 v123, 1.0, v123
	v_add_f32_e32 v126, 1.0, v126
	v_add_f32_e32 v127, 1.0, v127
	v_rcp_f32_e32 v166, v122
	v_rcp_f32_e32 v167, v123
	v_rcp_f32_e32 v126, v126
	v_rcp_f32_e32 v127, v127
	v_add_f32_e32 v118, 1.0, v118
	v_mul_f32_e32 v108, 0x3fb8aa3b, v108
	v_mul_f32_e32 v104, 0x3fb8aa3b, v104
	v_mul_f32_e32 v109, 0x3fb8aa3b, v109
	v_mul_f32_e32 v105, 0x3fb8aa3b, v105
	v_add_f32_e32 v116, 1.0, v116
	v_add_f32_e32 v117, 1.0, v117
	v_rcp_f32_e32 v171, v118
	v_exp_f32_e32 v108, v108
	v_exp_f32_e32 v104, v104
	v_exp_f32_e32 v109, v109
	v_exp_f32_e32 v105, v105
	v_mul_f32_e32 v106, 0x3fb8aa3b, v106
	v_rcp_f32_e32 v169, v116
	v_rcp_f32_e32 v170, v117
	v_rcp_f32_e32 v155, v155
	v_exp_f32_e32 v106, v106
	v_lshl_add_u64 v[112:113], s[6:7], 0, v[112:113]
	v_lshl_add_u64 v[112:113], v[112:113], 0, v[134:135]
	v_mul_f32_e32 v110, 0x3fb8aa3b, v110
	v_mul_f32_e32 v111, 0x3fb8aa3b, v111
	v_mul_f32_e32 v107, 0x3fb8aa3b, v107
	v_rcp_f32_e32 v129, v129
	v_rcp_f32_e32 v144, v144
	s_waitcnt vmcnt(0)
	v_pk_add_f32 v[122:123], v[130:131], 1.0 op_sel_hi:[1,0] neg_lo:[1,0] neg_hi:[1,0]
	v_pk_add_f32 v[120:121], v[156:157], 1.0 op_sel_hi:[1,0] neg_lo:[1,0] neg_hi:[1,0]
	v_pk_mul_f32 v[114:115], v[114:115], v[122:123]
	v_pk_mul_f32 v[130:131], v[124:125], v[120:121]
	v_cvt_pk_f16_f32 v124, v114, v115
	v_add_f32_e32 v114, 1.0, v165
	v_rcp_f32_e32 v114, v114
	v_add_f32_e32 v115, 1.0, v168
	v_pk_add_f32 v[116:117], v[132:133], 1.0 op_sel_hi:[1,0] neg_lo:[1,0] neg_hi:[1,0]
	v_pk_add_f32 v[118:119], v[158:159], 1.0 op_sel_hi:[1,0] neg_lo:[1,0] neg_hi:[1,0]
	v_rcp_f32_e32 v115, v115
	v_pk_mul_f32 v[126:127], v[126:127], v[116:117]
	v_pk_mul_f32 v[132:133], v[166:167], v[118:119]
	v_cvt_pk_f16_f32 v125, v126, v127
	v_cvt_pk_f16_f32 v126, v130, v131
	v_cvt_pk_f16_f32 v127, v132, v133
	global_store_dwordx4 v[112:113], v[124:127], off
	v_mul_f32_e32 v114, v114, v117
	v_add_f32_e32 v108, 1.0, v108
	v_mul_f32_e32 v125, v171, v116
	v_add_f32_e32 v104, 1.0, v104
	v_add_f32_e32 v109, 1.0, v109
	v_add_f32_e32 v105, 1.0, v105
	v_exp_f32_e32 v110, v110
	v_exp_f32_e32 v111, v111
	v_exp_f32_e32 v107, v107
	v_mul_f32_e32 v100, 0x3fb8aa3b, v100
	v_mul_f32_e32 v96, 0x3fb8aa3b, v96
	v_mul_f32_e32 v101, 0x3fb8aa3b, v101
	v_mul_f32_e32 v97, 0x3fb8aa3b, v97
	v_mul_f32_e32 v127, v155, v118
	v_mul_f32_e32 v115, v115, v119
	v_cvt_pk_f16_f32 v125, v125, v114
	v_or_b32_e32 v114, 16, v154
	v_rcp_f32_e32 v108, v108
	v_rcp_f32_e32 v104, v104
	v_rcp_f32_e32 v109, v109
	v_rcp_f32_e32 v105, v105
	v_add_f32_e32 v106, 1.0, v106
	v_exp_f32_e32 v100, v100
	v_exp_f32_e32 v96, v96
	v_exp_f32_e32 v101, v101
	v_exp_f32_e32 v97, v97
	v_mul_f32_e32 v98, 0x3fb8aa3b, v98
	v_cvt_pk_f16_f32 v127, v127, v115
	v_ashrrev_i32_e32 v115, 31, v114
	v_rcp_f32_e32 v106, v106
	v_exp_f32_e32 v98, v98
	v_lshlrev_b64 v[114:115], 12, v[114:115]
	v_mul_f32_e32 v156, v169, v122
	v_mul_f32_e32 v129, v129, v120
	v_mul_f32_e32 v157, v170, v123
	v_mul_f32_e32 v144, v144, v121
	v_lshl_add_u64 v[114:115], s[6:7], 0, v[114:115]
	v_add_f32_e32 v110, 1.0, v110
	v_add_f32_e32 v111, 1.0, v111
	v_add_f32_e32 v107, 1.0, v107
	v_mul_f32_e32 v102, 0x3fb8aa3b, v102
	v_mul_f32_e32 v103, 0x3fb8aa3b, v103
	v_mul_f32_e32 v99, 0x3fb8aa3b, v99
	v_cvt_pk_f16_f32 v124, v156, v157
	v_cvt_pk_f16_f32 v126, v129, v144
	v_lshl_add_u64 v[114:115], v[114:115], 0, v[134:135]
	v_mul_f32_e32 v108, v108, v122
	v_mul_f32_e32 v104, v104, v120
	v_mul_f32_e32 v109, v109, v123
	v_mul_f32_e32 v105, v105, v121
	v_rcp_f32_e32 v110, v110
	v_rcp_f32_e32 v111, v111
	v_rcp_f32_e32 v107, v107
	v_add_f32_e32 v100, 1.0, v100
	v_add_f32_e32 v96, 1.0, v96
	v_add_f32_e32 v101, 1.0, v101
	v_add_f32_e32 v97, 1.0, v97
	v_exp_f32_e32 v102, v102
	v_exp_f32_e32 v103, v103
	v_exp_f32_e32 v99, v99
;     __device__ __forceinline__ void operator()(const AccT& acc, const pg8::Unit& u, int wr, int wc, int fr, int fq) const {
;     ...
;                     for (int m = 0; m < 4; ++m) {
;                         const f32x4 a = acc[ai][bj][m][0], b = acc[ai][bj][m][1]; float g[8];
; #pragma unroll
;                         for (int j = 0; j < 4; ++j) { g[j] = (1.f - l0[j]) * __builtin_amdgcn_rcpf(1.f + __expf(a[j])); g[4 + j] = (1.f - l1[j]) * __builtin_amdgcn_rcpf(1.f + __expf(b[j])); }
;                         u32x4 w; w.x = pk_h2(g[0], g[1]); w.y = pk_h2(g[2], g[3]); w.z = pk_h2(g[4], g[5]); w.w = pk_h2(g[6], g[7]);
;                         *(u32x4*)(G + (size_t)(row0 + ai * 128 + m * 16) * 2048 + col) = w;
;                     }
	global_store_dwordx4 v[114:115], v[124:127], off
	v_rcp_f32_e32 v100, v100
	v_rcp_f32_e32 v96, v96
	v_mul_f32_e32 v124, v106, v118
	v_cvt_pk_f16_f32 v106, v108, v109
	v_cvt_pk_f16_f32 v108, v104, v105
	v_or_b32_e32 v104, 32, v154
	v_rcp_f32_e32 v101, v101
	v_rcp_f32_e32 v97, v97
	v_add_f32_e32 v98, 1.0, v98
	v_mul_f32_e32 v88, 0x3fb8aa3b, v88
	v_mul_f32_e32 v93, 0x3fb8aa3b, v93
	v_ashrrev_i32_e32 v105, 31, v104
	v_rcp_f32_e32 v98, v98
	v_exp_f32_e32 v88, v88
	v_exp_f32_e32 v93, v93
	v_lshlrev_b64 v[104:105], 12, v[104:105]
	v_mul_f32_e32 v110, v110, v116
	v_mul_f32_e32 v111, v111, v117
	v_mul_f32_e32 v125, v107, v119
	v_lshl_add_u64 v[104:105], s[6:7], 0, v[104:105]
	v_add_f32_e32 v102, 1.0, v102
	v_add_f32_e32 v103, 1.0, v103
	v_add_f32_e32 v99, 1.0, v99
	v_cvt_pk_f16_f32 v107, v110, v111
	v_cvt_pk_f16_f32 v109, v124, v125
	v_lshl_add_u64 v[104:105], v[104:105], 0, v[134:135]
	v_mul_f32_e32 v100, v100, v122
	v_mul_f32_e32 v96, v96, v120
	v_mul_f32_e32 v101, v101, v123
	v_mul_f32_e32 v97, v97, v121
	v_rcp_f32_e32 v102, v102
	v_rcp_f32_e32 v103, v103
	v_rcp_f32_e32 v99, v99
	global_store_dwordx4 v[104:105], v[106:109], off
	v_add_f32_e32 v88, 1.0, v88
	v_add_f32_e32 v93, 1.0, v93
	v_mul_f32_e32 v106, v98, v118
	v_cvt_pk_f16_f32 v98, v100, v101
	v_cvt_pk_f16_f32 v100, v96, v97
	v_or_b32_e32 v96, 48, v154
	v_mul_f32_e32 v89, 0x3fb8aa3b, v89
	v_ashrrev_i32_e32 v97, 31, v96
	v_rcp_f32_e32 v88, v88
	v_rcp_f32_e32 v93, v93
	v_exp_f32_e32 v89, v89
	v_lshlrev_b64 v[96:97], 12, v[96:97]
	v_mul_f32_e32 v102, v102, v116
	v_mul_f32_e32 v103, v103, v117
	v_mul_f32_e32 v107, v99, v119
	v_lshl_add_u64 v[96:97], s[6:7], 0, v[96:97]
	v_cvt_pk_f16_f32 v99, v102, v103
	v_cvt_pk_f16_f32 v101, v106, v107
	v_lshl_add_u64 v[96:97], v[96:97], 0, v[134:135]
	global_store_dwordx4 v[96:97], v[98:101], off
	v_add_f32_e32 v89, 1.0, v89
	v_rcp_f32_e32 v89, v89
	v_mul_f32_e32 v98, v88, v120
	v_mul_f32_e32 v88, v93, v123
	v_mul_f32_e32 v93, 0x3fb8aa3b, v94
	v_exp_f32_e32 v93, v93
	v_mul_f32_e32 v92, 0x3fb8aa3b, v92
	v_exp_f32_e32 v92, v92
	v_mul_f32_e32 v90, 0x3fb8aa3b, v90
	v_mul_f32_e32 v94, v89, v121
	v_add_f32_e32 v89, 1.0, v93
	v_mul_f32_e32 v93, 0x3fb8aa3b, v95
	v_mul_f32_e32 v91, 0x3fb8aa3b, v91
	v_exp_f32_e32 v90, v90
	v_exp_f32_e32 v93, v93
	v_exp_f32_e32 v91, v91
	v_mul_f32_e32 v80, 0x3fb8aa3b, v80
	v_mul_f32_e32 v85, 0x3fb8aa3b, v85
	v_exp_f32_e32 v80, v80
	v_exp_f32_e32 v85, v85
	v_add_f32_e32 v92, 1.0, v92
	v_rcp_f32_e32 v92, v92
	v_add_f32_e32 v90, 1.0, v90
	v_add_f32_e32 v93, 1.0, v93
	v_add_f32_e32 v91, 1.0, v91
	v_rcp_f32_e32 v89, v89
	v_rcp_f32_e32 v90, v90
	v_rcp_f32_e32 v93, v93
	v_rcp_f32_e32 v91, v91
	v_add_f32_e32 v80, 1.0, v80
	v_add_f32_e32 v85, 1.0, v85
	v_mul_f32_e32 v81, 0x3fb8aa3b, v81
	v_rcp_f32_e32 v80, v80
	v_rcp_f32_e32 v85, v85
	v_exp_f32_e32 v81, v81
	v_mul_f32_e32 v92, v92, v122
	v_mul_f32_e32 v89, v89, v116
	v_mul_f32_e32 v95, v90, v118
	v_mul_f32_e32 v90, v93, v117
	v_mul_f32_e32 v91, v91, v119
	v_cvt_pk_f16_f32 v88, v92, v88
	v_add_co_u32_e32 v92, vcc, s92, v112
	v_cvt_pk_f16_f32 v89, v89, v90
	v_cvt_pk_f16_f32 v90, v98, v94
	v_cvt_pk_f16_f32 v91, v95, v91
	v_addc_co_u32_e32 v93, vcc, 0, v113, vcc
	global_store_dwordx4 v[92:93], v[88:91], off
	v_add_f32_e32 v81, 1.0, v81
	v_rcp_f32_e32 v81, v81
	v_mul_f32_e32 v88, v80, v120
	v_mul_f32_e32 v80, v85, v123
	v_mul_f32_e32 v85, 0x3fb8aa3b, v86
	v_exp_f32_e32 v85, v85
	v_mul_f32_e32 v84, 0x3fb8aa3b, v84
	v_exp_f32_e32 v84, v84
	v_mul_f32_e32 v82, 0x3fb8aa3b, v82
	v_mul_f32_e32 v86, v81, v121
	v_add_f32_e32 v81, 1.0, v85
	v_mul_f32_e32 v85, 0x3fb8aa3b, v87
	v_mul_f32_e32 v83, 0x3fb8aa3b, v83
	v_exp_f32_e32 v82, v82
	v_exp_f32_e32 v85, v85
	v_exp_f32_e32 v83, v83
	v_mul_f32_e32 v72, 0x3fb8aa3b, v72
	v_mul_f32_e32 v77, 0x3fb8aa3b, v77
	v_exp_f32_e32 v72, v72
	v_exp_f32_e32 v77, v77
	v_add_f32_e32 v84, 1.0, v84
	v_rcp_f32_e32 v84, v84
	v_add_f32_e32 v82, 1.0, v82
	v_add_f32_e32 v85, 1.0, v85
	v_add_f32_e32 v83, 1.0, v83
	v_rcp_f32_e32 v81, v81
	v_rcp_f32_e32 v82, v82
	v_rcp_f32_e32 v85, v85
	v_rcp_f32_e32 v83, v83
	v_add_f32_e32 v72, 1.0, v72
	v_add_f32_e32 v77, 1.0, v77
	v_mul_f32_e32 v73, 0x3fb8aa3b, v73
	v_rcp_f32_e32 v72, v72
	v_rcp_f32_e32 v77, v77
	v_exp_f32_e32 v73, v73
	v_mul_f32_e32 v84, v84, v122
	v_mul_f32_e32 v81, v81, v116
	v_mul_f32_e32 v87, v82, v118
	v_mul_f32_e32 v82, v85, v117
	v_mul_f32_e32 v83, v83, v119
	v_cvt_pk_f16_f32 v80, v84, v80
	v_add_co_u32_e32 v84, vcc, s93, v112
	v_cvt_pk_f16_f32 v81, v81, v82
	v_cvt_pk_f16_f32 v82, v88, v86
	v_cvt_pk_f16_f32 v83, v87, v83
	v_addc_co_u32_e32 v85, vcc, 0, v113, vcc
	global_store_dwordx4 v[84:85], v[80:83], off
	v_add_f32_e32 v73, 1.0, v73
	v_rcp_f32_e32 v73, v73
	v_mul_f32_e32 v80, v72, v120
	v_mul_f32_e32 v72, v77, v123
	v_mul_f32_e32 v77, 0x3fb8aa3b, v78
	v_exp_f32_e32 v77, v77
	v_mul_f32_e32 v76, 0x3fb8aa3b, v76
	v_exp_f32_e32 v76, v76
	v_mul_f32_e32 v74, 0x3fb8aa3b, v74
	v_mul_f32_e32 v78, v73, v121
	v_add_f32_e32 v73, 1.0, v77
	v_mul_f32_e32 v77, 0x3fb8aa3b, v79
	v_mul_f32_e32 v75, 0x3fb8aa3b, v75
	v_exp_f32_e32 v74, v74
	v_exp_f32_e32 v77, v77
	v_exp_f32_e32 v75, v75
	v_mul_f32_e32 v64, 0x3fb8aa3b, v64
	v_mul_f32_e32 v69, 0x3fb8aa3b, v69
	v_exp_f32_e32 v64, v64
	v_exp_f32_e32 v69, v69
	v_add_f32_e32 v76, 1.0, v76
	v_rcp_f32_e32 v76, v76
	v_add_f32_e32 v74, 1.0, v74
	v_add_f32_e32 v77, 1.0, v77
	v_add_f32_e32 v75, 1.0, v75
	v_rcp_f32_e32 v73, v73
	v_rcp_f32_e32 v74, v74
	v_rcp_f32_e32 v77, v77
	v_rcp_f32_e32 v75, v75
	v_add_f32_e32 v64, 1.0, v64
	v_add_f32_e32 v69, 1.0, v69
	v_mul_f32_e32 v65, 0x3fb8aa3b, v65
	v_rcp_f32_e32 v64, v64
	v_rcp_f32_e32 v69, v69
	v_exp_f32_e32 v65, v65
	v_mul_f32_e32 v76, v76, v122
;     __device__ __forceinline__ void operator()(const AccT& acc, const pg8::Unit& u, int wr, int wc, int fr, int fq) const {
;     ...
;             for (int bj = 0; bj < 2; ++bj) {
;                 const int col = pn * 256 + bj * 128 + cl;
;                 const f32x4 l0 = *(const f32x4*)(lb + col), l1 = *(const f32x4*)(lb + col + 4);
; #pragma unroll
;                 for (int ai = 0; ai < 2; ++ai)
; #pragma unroll
;                     for (int m = 0; m < 4; ++m) {
;                         const f32x4 a = acc[ai][bj][m][0], b = acc[ai][bj][m][1]; float g[8];
; #pragma unroll
;                         for (int j = 0; j < 4; ++j) { g[j] = (1.f - l0[j]) * __builtin_amdgcn_rcpf(1.f + __expf(a[j])); g[4 + j] = (1.f - l1[j]) * __builtin_amdgcn_rcpf(1.f + __expf(b[j])); }
;                         u32x4 w; w.x = pk_h2(g[0], g[1]); w.y = pk_h2(g[2], g[3]); w.z = pk_h2(g[4], g[5]); w.w = pk_h2(g[6], g[7]);
;                         *(u32x4*)(G + (size_t)(row0 + ai * 128 + m * 16) * 2048 + col) = w;
;                     }
	v_mul_f32_e32 v73, v73, v116
	v_mul_f32_e32 v79, v74, v118
	v_mul_f32_e32 v74, v77, v117
	v_mul_f32_e32 v75, v75, v119
	v_cvt_pk_f16_f32 v72, v76, v72
	v_add_co_u32_e32 v76, vcc, s94, v112
	v_cvt_pk_f16_f32 v73, v73, v74
	v_cvt_pk_f16_f32 v74, v80, v78
	v_cvt_pk_f16_f32 v75, v79, v75
	v_addc_co_u32_e32 v77, vcc, 0, v113, vcc
	global_store_dwordx4 v[76:77], v[72:75], off
	v_add_f32_e32 v65, 1.0, v65
	v_rcp_f32_e32 v65, v65
	v_mul_f32_e32 v72, v64, v120
	v_mul_f32_e32 v64, v69, v123
	v_mul_f32_e32 v69, 0x3fb8aa3b, v70
	v_exp_f32_e32 v69, v69
	v_mul_f32_e32 v68, 0x3fb8aa3b, v68
	v_exp_f32_e32 v68, v68
	v_mul_f32_e32 v66, 0x3fb8aa3b, v66
	v_mul_f32_e32 v70, v65, v121
	v_add_f32_e32 v65, 1.0, v69
	v_mul_f32_e32 v69, 0x3fb8aa3b, v71
	v_mul_f32_e32 v67, 0x3fb8aa3b, v67
	v_exp_f32_e32 v66, v66
	v_exp_f32_e32 v69, v69
	v_exp_f32_e32 v67, v67
	v_add_f32_e32 v68, 1.0, v68
	v_rcp_f32_e32 v68, v68
	v_add_f32_e32 v66, 1.0, v66
	v_add_f32_e32 v69, 1.0, v69
	v_add_f32_e32 v67, 1.0, v67
	v_rcp_f32_e32 v65, v65
	v_rcp_f32_e32 v66, v66
	v_rcp_f32_e32 v69, v69
	v_rcp_f32_e32 v67, v67
	v_mul_f32_e32 v68, v68, v122
	v_mul_f32_e32 v65, v65, v116
	v_mul_f32_e32 v71, v66, v118
	v_mul_f32_e32 v66, v69, v117
	v_mul_f32_e32 v67, v67, v119
	v_cvt_pk_f16_f32 v64, v68, v64
	v_add_co_u32_e32 v68, vcc, s95, v112
	v_cvt_pk_f16_f32 v65, v65, v66
	v_cvt_pk_f16_f32 v66, v72, v70
	v_cvt_pk_f16_f32 v67, v71, v67
	v_addc_co_u32_e32 v69, vcc, 0, v113, vcc
	global_store_dwordx4 v[68:69], v[64:67], off
	v_mul_f32_e32 v61, 0x3fb8aa3b, v61
	v_exp_f32_e32 v61, v61
	v_or_b32_e32 v64, 0x80, v128
	v_ashrrev_i32_e32 v65, 31, v64
	v_lshl_add_u64 v[64:65], v[64:65], 2, s[20:21]
	s_nop 0
	s_nop 0
	v_mul_f32_e32 v57, 0x3fb8aa3b, v57
	v_mul_f32_e32 v60, 0x3fb8aa3b, v60
	v_mul_f32_e32 v56, 0x3fb8aa3b, v56
	v_exp_f32_e32 v81, v57
	v_add_f32_e32 v57, 1.0, v61
	v_mul_f32_e32 v61, 0x3fb8aa3b, v62
	v_exp_f32_e32 v60, v60
	v_exp_f32_e32 v80, v56
	v_exp_f32_e32 v61, v61
	v_mul_f32_e32 v58, 0x3fb8aa3b, v58
	v_exp_f32_e32 v62, v58
	v_add_f32_e32 v56, 1.0, v60
	v_add_f32_e32 v60, 1.0, v80
	v_add_f32_e32 v58, 1.0, v61
	v_mul_f32_e32 v61, 0x3fb8aa3b, v63
	v_rcp_f32_e32 v80, v60
	v_add_f32_e32 v60, 1.0, v81
	v_exp_f32_e32 v61, v61
	v_mul_f32_e32 v59, 0x3fb8aa3b, v59
	v_rcp_f32_e32 v81, v60
	v_add_f32_e32 v60, 1.0, v62
	v_exp_f32_e32 v62, v59
	v_rcp_f32_e32 v56, v56
	v_rcp_f32_e32 v57, v57
	v_add_f32_e32 v59, 1.0, v61
	v_mul_f32_e32 v48, 0x3fb8aa3b, v48
	v_mul_f32_e32 v53, 0x3fb8aa3b, v53
	v_rcp_f32_e32 v58, v58
	v_rcp_f32_e32 v82, v60
	v_rcp_f32_e32 v59, v59
	v_add_f32_e32 v60, 1.0, v62
	v_exp_f32_e32 v48, v48
	v_exp_f32_e32 v53, v53
	v_rcp_f32_e32 v83, v60
	v_mul_f32_e32 v49, 0x3fb8aa3b, v49
	v_add_f32_e32 v48, 1.0, v48
	v_add_f32_e32 v53, 1.0, v53
	v_rcp_f32_e32 v48, v48
	v_rcp_f32_e32 v53, v53
	v_exp_f32_e32 v49, v49
	v_mul_f32_e32 v52, 0x3fb8aa3b, v52
	v_mul_f32_e32 v50, 0x3fb8aa3b, v50
	v_mul_f32_e32 v51, 0x3fb8aa3b, v51
	v_add_f32_e32 v49, 1.0, v49
	v_rcp_f32_e32 v49, v49
	v_exp_f32_e32 v52, v52
	v_exp_f32_e32 v50, v50
	v_exp_f32_e32 v51, v51
	v_mul_f32_e32 v40, 0x3fb8aa3b, v40
	v_mul_f32_e32 v45, 0x3fb8aa3b, v45
	v_exp_f32_e32 v40, v40
	v_exp_f32_e32 v45, v45
	v_add_f32_e32 v52, 1.0, v52
	v_add_f32_e32 v50, 1.0, v50
	v_add_f32_e32 v51, 1.0, v51
	v_rcp_f32_e32 v52, v52
	v_rcp_f32_e32 v50, v50
	v_rcp_f32_e32 v51, v51
	v_add_f32_e32 v40, 1.0, v40
	v_add_f32_e32 v45, 1.0, v45
	v_mul_f32_e32 v41, 0x3fb8aa3b, v41
	v_rcp_f32_e32 v40, v40
	v_rcp_f32_e32 v45, v45
	v_exp_f32_e32 v41, v41
	v_mul_f32_e32 v44, 0x3fb8aa3b, v44
	v_mul_f32_e32 v42, 0x3fb8aa3b, v42
	v_mul_f32_e32 v43, 0x3fb8aa3b, v43
	v_add_f32_e32 v41, 1.0, v41
	v_rcp_f32_e32 v41, v41
	v_exp_f32_e32 v44, v44
	v_exp_f32_e32 v42, v42
	v_exp_f32_e32 v43, v43
	v_mul_f32_e32 v32, 0x3fb8aa3b, v32
	v_mul_f32_e32 v37, 0x3fb8aa3b, v37
	v_exp_f32_e32 v32, v32
	v_exp_f32_e32 v37, v37
	v_add_f32_e32 v44, 1.0, v44
	v_add_f32_e32 v42, 1.0, v42
	s_nop 0
	v_pk_add_f32 v[60:61], v[226:227], 1.0 op_sel_hi:[1,0] neg_lo:[1,0] neg_hi:[1,0]
	v_pk_add_f32 v[62:63], v[230:231], 1.0 op_sel_hi:[1,0] neg_lo:[1,0] neg_hi:[1,0]
	v_pk_mul_f32 v[56:57], v[56:57], v[60:61]
	v_mul_f32_e32 v52, v52, v60
	v_cvt_pk_f16_f32 v72, v56, v57
	v_pk_add_f32 v[56:57], v[228:229], 1.0 op_sel_hi:[1,0] neg_lo:[1,0] neg_hi:[1,0]
	v_add_f32_e32 v43, 1.0, v43
	v_pk_mul_f32 v[58:59], v[58:59], v[56:57]
	v_rcp_f32_e32 v44, v44
	v_cvt_pk_f16_f32 v73, v58, v59
	v_pk_mul_f32 v[58:59], v[80:81], v[62:63]
	v_rcp_f32_e32 v42, v42
	v_cvt_pk_f16_f32 v74, v58, v59
	v_pk_add_f32 v[58:59], v[232:233], 1.0 op_sel_hi:[1,0] neg_lo:[1,0] neg_hi:[1,0]
	v_rcp_f32_e32 v43, v43
	v_pk_mul_f32 v[76:77], v[82:83], v[58:59]
	v_mul_f32_e32 v51, v51, v59
	v_cvt_pk_f16_f32 v75, v76, v77
	global_store_dwordx4 v[112:113], v[72:75], off offset:256
	v_add_f32_e32 v32, 1.0, v32
	v_add_f32_e32 v37, 1.0, v37
	v_mul_f32_e32 v72, v48, v62
	v_mul_f32_e32 v48, v53, v61
	v_mul_f32_e32 v53, 0x3fb8aa3b, v54
	v_exp_f32_e32 v53, v53
	v_mul_f32_e32 v54, v49, v63
	v_cvt_pk_f16_f32 v48, v52, v48
	v_mul_f32_e32 v33, 0x3fb8aa3b, v33
	v_add_f32_e32 v49, 1.0, v53
	v_mul_f32_e32 v53, 0x3fb8aa3b, v55
	v_exp_f32_e32 v53, v53
	v_rcp_f32_e32 v49, v49
	v_mul_f32_e32 v55, v50, v58
	v_cvt_pk_f16_f32 v51, v55, v51
	v_add_f32_e32 v53, 1.0, v53
	v_rcp_f32_e32 v53, v53
	v_mul_f32_e32 v49, v49, v56
	v_rcp_f32_e32 v32, v32
	v_rcp_f32_e32 v37, v37
	v_mul_f32_e32 v50, v53, v57
	v_cvt_pk_f16_f32 v49, v49, v50
	v_cvt_pk_f16_f32 v50, v72, v54
	global_store_dwordx4 v[114:115], v[48:51], off offset:256
	v_exp_f32_e32 v33, v33
	v_mul_f32_e32 v44, v44, v60
	v_mul_f32_e32 v48, v40, v62
	v_mul_f32_e32 v40, v45, v61
	v_mul_f32_e32 v45, 0x3fb8aa3b, v46
	v_exp_f32_e32 v45, v45
;     __device__ __forceinline__ void operator()(const AccT& acc, const pg8::Unit& u, int wr, int wc, int fr, int fq) const {
;     ...
;                     for (int m = 0; m < 4; ++m) {
;                         const f32x4 a = acc[ai][bj][m][0], b = acc[ai][bj][m][1]; float g[8];
; #pragma unroll
;                         for (int j = 0; j < 4; ++j) { g[j] = (1.f - l0[j]) * __builtin_amdgcn_rcpf(1.f + __expf(a[j])); g[4 + j] = (1.f - l1[j]) * __builtin_amdgcn_rcpf(1.f + __expf(b[j])); }
;                         u32x4 w; w.x = pk_h2(g[0], g[1]); w.y = pk_h2(g[2], g[3]); w.z = pk_h2(g[4], g[5]); w.w = pk_h2(g[6], g[7]);
;                         *(u32x4*)(G + (size_t)(row0 + ai * 128 + m * 16) * 2048 + col) = w;
;                     }
	v_mul_f32_e32 v46, v41, v63
	v_mul_f32_e32 v43, v43, v59
	v_cvt_pk_f16_f32 v40, v44, v40
	v_add_f32_e32 v41, 1.0, v45
	v_mul_f32_e32 v45, 0x3fb8aa3b, v47
	v_exp_f32_e32 v45, v45
	v_rcp_f32_e32 v41, v41
	v_mul_f32_e32 v47, v42, v58
	v_cvt_pk_f16_f32 v43, v47, v43
	v_add_f32_e32 v45, 1.0, v45
	v_rcp_f32_e32 v45, v45
	v_mul_f32_e32 v41, v41, v56
	v_add_f32_e32 v33, 1.0, v33
	v_rcp_f32_e32 v33, v33
	v_mul_f32_e32 v42, v45, v57
	v_cvt_pk_f16_f32 v41, v41, v42
	v_cvt_pk_f16_f32 v42, v48, v46
	global_store_dwordx4 v[104:105], v[40:43], off offset:256
	v_mul_f32_e32 v36, 0x3fb8aa3b, v36
	v_mul_f32_e32 v34, 0x3fb8aa3b, v34
	v_mul_f32_e32 v40, v32, v62
	v_mul_f32_e32 v32, v37, v61
	v_mul_f32_e32 v37, 0x3fb8aa3b, v38
	v_exp_f32_e32 v37, v37
	v_mul_f32_e32 v38, v33, v63
	v_mul_f32_e32 v35, 0x3fb8aa3b, v35
	v_exp_f32_e32 v36, v36
	v_add_f32_e32 v33, 1.0, v37
	v_mul_f32_e32 v37, 0x3fb8aa3b, v39
	v_exp_f32_e32 v34, v34
	v_exp_f32_e32 v37, v37
	v_exp_f32_e32 v35, v35
	v_mul_f32_e32 v24, 0x3fb8aa3b, v24
	v_mul_f32_e32 v29, 0x3fb8aa3b, v29
	v_exp_f32_e32 v24, v24
	v_exp_f32_e32 v29, v29
	v_add_f32_e32 v36, 1.0, v36
	v_add_f32_e32 v34, 1.0, v34
	v_add_f32_e32 v37, 1.0, v37
	v_add_f32_e32 v35, 1.0, v35
	v_rcp_f32_e32 v36, v36
	v_rcp_f32_e32 v33, v33
	v_rcp_f32_e32 v34, v34
	v_rcp_f32_e32 v37, v37
	v_rcp_f32_e32 v35, v35
	v_add_f32_e32 v24, 1.0, v24
	v_add_f32_e32 v29, 1.0, v29
	v_mul_f32_e32 v25, 0x3fb8aa3b, v25
	v_rcp_f32_e32 v24, v24
	v_rcp_f32_e32 v29, v29
	v_exp_f32_e32 v25, v25
	v_mul_f32_e32 v36, v36, v60
	v_mul_f32_e32 v33, v33, v56
	v_mul_f32_e32 v39, v34, v58
	v_mul_f32_e32 v34, v37, v57
	v_mul_f32_e32 v35, v35, v59
	v_cvt_pk_f16_f32 v32, v36, v32
	v_cvt_pk_f16_f32 v33, v33, v34
	v_cvt_pk_f16_f32 v34, v40, v38
	v_cvt_pk_f16_f32 v35, v39, v35
	global_store_dwordx4 v[96:97], v[32:35], off offset:256
	v_add_f32_e32 v25, 1.0, v25
	v_rcp_f32_e32 v25, v25
	v_mul_f32_e32 v32, v24, v62
	v_mul_f32_e32 v24, v29, v61
	v_mul_f32_e32 v29, 0x3fb8aa3b, v30
	v_exp_f32_e32 v29, v29
	v_mul_f32_e32 v28, 0x3fb8aa3b, v28
	v_mul_f32_e32 v26, 0x3fb8aa3b, v26
	v_mul_f32_e32 v30, v25, v63
	v_add_f32_e32 v25, 1.0, v29
	v_mul_f32_e32 v29, 0x3fb8aa3b, v31
	v_mul_f32_e32 v27, 0x3fb8aa3b, v27
	v_exp_f32_e32 v28, v28
	v_exp_f32_e32 v26, v26
	v_exp_f32_e32 v29, v29
	v_exp_f32_e32 v27, v27
	v_mul_f32_e32 v16, 0x3fb8aa3b, v16
	v_mul_f32_e32 v21, 0x3fb8aa3b, v21
	v_exp_f32_e32 v16, v16
	v_exp_f32_e32 v21, v21
	v_add_f32_e32 v28, 1.0, v28
	v_add_f32_e32 v26, 1.0, v26
	v_add_f32_e32 v29, 1.0, v29
	v_add_f32_e32 v27, 1.0, v27
	v_rcp_f32_e32 v28, v28
	v_rcp_f32_e32 v25, v25
	v_rcp_f32_e32 v26, v26
	v_rcp_f32_e32 v29, v29
	v_rcp_f32_e32 v27, v27
	v_add_f32_e32 v16, 1.0, v16
	v_add_f32_e32 v21, 1.0, v21
	v_mul_f32_e32 v17, 0x3fb8aa3b, v17
	v_rcp_f32_e32 v16, v16
	v_rcp_f32_e32 v21, v21
	v_exp_f32_e32 v17, v17
	s_mov_b64 s[4:5], 0x80000
	v_mul_f32_e32 v28, v28, v60
	v_mul_f32_e32 v25, v25, v56
	v_mul_f32_e32 v31, v26, v58
	v_mul_f32_e32 v26, v29, v57
	v_mul_f32_e32 v27, v27, v59
	v_lshl_add_u64 v[70:71], v[112:113], 0, s[4:5]
	v_cvt_pk_f16_f32 v24, v28, v24
	v_cvt_pk_f16_f32 v25, v25, v26
	v_cvt_pk_f16_f32 v26, v32, v30
	v_cvt_pk_f16_f32 v27, v31, v27
	global_store_dwordx4 v[70:71], v[24:27], off offset:256
	v_add_f32_e32 v17, 1.0, v17
	v_rcp_f32_e32 v17, v17
	v_mul_f32_e32 v24, v16, v62
	v_mul_f32_e32 v16, v21, v61
	v_mul_f32_e32 v21, 0x3fb8aa3b, v22
	v_exp_f32_e32 v21, v21
	v_mul_f32_e32 v20, 0x3fb8aa3b, v20
	v_mul_f32_e32 v18, 0x3fb8aa3b, v18
	v_mul_f32_e32 v22, v17, v63
	v_add_f32_e32 v17, 1.0, v21
	v_mul_f32_e32 v21, 0x3fb8aa3b, v23
	v_mul_f32_e32 v19, 0x3fb8aa3b, v19
	v_exp_f32_e32 v20, v20
	v_exp_f32_e32 v18, v18
	v_exp_f32_e32 v21, v21
	v_exp_f32_e32 v19, v19
	v_mul_f32_e32 v8, 0x3fb8aa3b, v8
	v_mul_f32_e32 v13, 0x3fb8aa3b, v13
	v_exp_f32_e32 v8, v8
	v_exp_f32_e32 v13, v13
	v_add_f32_e32 v20, 1.0, v20
	v_add_f32_e32 v18, 1.0, v18
	v_add_f32_e32 v21, 1.0, v21
	v_add_f32_e32 v19, 1.0, v19
	v_rcp_f32_e32 v20, v20
	v_rcp_f32_e32 v17, v17
	v_rcp_f32_e32 v18, v18
	v_rcp_f32_e32 v21, v21
	v_rcp_f32_e32 v19, v19
	v_add_f32_e32 v8, 1.0, v8
	v_add_f32_e32 v13, 1.0, v13
	v_mul_f32_e32 v9, 0x3fb8aa3b, v9
	v_rcp_f32_e32 v8, v8
	v_rcp_f32_e32 v13, v13
	v_exp_f32_e32 v9, v9
	v_mul_f32_e32 v20, v20, v60
	v_mul_f32_e32 v17, v17, v56
	v_mul_f32_e32 v23, v18, v58
	v_mul_f32_e32 v18, v21, v57
	v_mul_f32_e32 v19, v19, v59
	v_lshl_add_u64 v[68:69], v[112:113], 0, s[40:41]
	v_cvt_pk_f16_f32 v16, v20, v16
	v_cvt_pk_f16_f32 v17, v17, v18
	v_cvt_pk_f16_f32 v18, v24, v22
	v_cvt_pk_f16_f32 v19, v23, v19
	global_store_dwordx4 v[68:69], v[16:19], off offset:256
	v_add_f32_e32 v9, 1.0, v9
	v_rcp_f32_e32 v9, v9
	v_mul_f32_e32 v16, v8, v62
	v_mul_f32_e32 v8, v13, v61
	v_mul_f32_e32 v13, 0x3fb8aa3b, v14
	v_exp_f32_e32 v13, v13
	v_mul_f32_e32 v12, 0x3fb8aa3b, v12
	v_mul_f32_e32 v10, 0x3fb8aa3b, v10
	v_mul_f32_e32 v14, v9, v63
	v_add_f32_e32 v9, 1.0, v13
	v_mul_f32_e32 v13, 0x3fb8aa3b, v15
	v_mul_f32_e32 v11, 0x3fb8aa3b, v11
	v_exp_f32_e32 v12, v12
	v_exp_f32_e32 v10, v10
	v_exp_f32_e32 v13, v13
	v_exp_f32_e32 v11, v11
	v_mul_f32_e32 v0, 0x3fb8aa3b, v0
	v_mul_f32_e32 v5, 0x3fb8aa3b, v5
	v_exp_f32_e32 v0, v0
	v_exp_f32_e32 v5, v5
	v_add_f32_e32 v12, 1.0, v12
	v_add_f32_e32 v10, 1.0, v10
	v_add_f32_e32 v13, 1.0, v13
	v_add_f32_e32 v11, 1.0, v11
	v_rcp_f32_e32 v12, v12
	v_rcp_f32_e32 v9, v9
	v_rcp_f32_e32 v10, v10
	v_rcp_f32_e32 v13, v13
	v_rcp_f32_e32 v11, v11
	v_add_f32_e32 v0, 1.0, v0
	v_add_f32_e32 v5, 1.0, v5
	v_mul_f32_e32 v1, 0x3fb8aa3b, v1
	v_rcp_f32_e32 v0, v0
	v_rcp_f32_e32 v5, v5
	v_exp_f32_e32 v1, v1
	v_mul_f32_e32 v12, v12, v60
	v_mul_f32_e32 v9, v9, v56
	v_mul_f32_e32 v15, v10, v58
	v_mul_f32_e32 v10, v13, v57
	v_mul_f32_e32 v11, v11, v59
	v_lshl_add_u64 v[66:67], v[112:113], 0, s[42:43]
	v_cvt_pk_f16_f32 v8, v12, v8
	v_cvt_pk_f16_f32 v9, v9, v10
	v_cvt_pk_f16_f32 v10, v16, v14
	v_cvt_pk_f16_f32 v11, v15, v11
	global_store_dwordx4 v[66:67], v[8:11], off offset:256
	v_add_f32_e32 v1, 1.0, v1
	v_rcp_f32_e32 v1, v1
	v_mul_f32_e32 v8, v0, v62
	v_mul_f32_e32 v0, v5, v61
	v_mul_f32_e32 v5, 0x3fb8aa3b, v6
	v_exp_f32_e32 v5, v5
	v_mul_f32_e32 v4, 0x3fb8aa3b, v4
	v_mul_f32_e32 v2, 0x3fb8aa3b, v2
	v_mul_f32_e32 v6, v1, v63
	v_add_f32_e32 v1, 1.0, v5
	v_mul_f32_e32 v5, 0x3fb8aa3b, v7
	v_mul_f32_e32 v3, 0x3fb8aa3b, v3
	v_exp_f32_e32 v4, v4
	v_exp_f32_e32 v2, v2
	v_exp_f32_e32 v5, v5
	v_exp_f32_e32 v3, v3
	v_add_f32_e32 v4, 1.0, v4
	v_add_f32_e32 v2, 1.0, v2
	v_add_f32_e32 v5, 1.0, v5
	v_add_f32_e32 v3, 1.0, v3
	v_rcp_f32_e32 v4, v4
	v_rcp_f32_e32 v1, v1
	v_rcp_f32_e32 v2, v2
	v_rcp_f32_e32 v5, v5
	v_rcp_f32_e32 v3, v3
	v_mul_f32_e32 v4, v4, v60
	v_mul_f32_e32 v1, v1, v56
	v_mul_f32_e32 v7, v2, v58
	v_mul_f32_e32 v2, v5, v57
	v_mul_f32_e32 v3, v3, v59
	v_lshl_add_u64 v[64:65], v[112:113], 0, s[44:45]
	v_cvt_pk_f16_f32 v0, v4, v0
	v_cvt_pk_f16_f32 v1, v1, v2
	v_cvt_pk_f16_f32 v2, v8, v6
	v_cvt_pk_f16_f32 v3, v7, v3
	global_store_dwordx4 v[64:65], v[0:3], off offset:256
	s_branch .LBB0_231
